# ring4+R4+Qreg + K/V tiles via direct-to-LDS loads (global_load_lds) 2 steps ahead: no staging VGPRs, no ds_write, no VALU address math
# speedup vs baseline: 1.0545x; 1.0369x over previous
.LBB0_397:
	s_and_b32 s45, s0, 15
	s_ashr_i32 s37, s36, 31
	s_mul_i32 s3, s36, 0x1800
	s_mul_hi_i32 s1, s36, 0x1800
	s_add_u32 s3, s78, s3
	v_readlane_b32 s2, v252, 50
	s_addc_u32 s1, s2, s1
	s_lshl_b32 s5, s45, 7
	s_add_u32 s30, s3, s5
	s_addc_u32 s31, s1, 0
	v_readlane_b32 s2, v250, 19
	v_readlane_b32 s3, v250, 20
	s_add_u32 s28, s2, s5
	v_mov_b32_e32 v6, v168
	s_addc_u32 s29, s3, 0
	s_lshl_b32 s0, s0, 7
	s_and_b32 s0, s0, 0x700
	v_ashrrev_i32_e32 v0, 6, v6
	v_and_b32_e32 v62, 63, v6
	v_and_b32_e32 v1, 0x3fffffc0, v6
	v_and_b32_e32 v200, 31, v6
	v_lshl_add_u32 v175, v1, 2, v192
	v_lshl_add_u32 v1, v0, 12, v192
	v_lshlrev_b32_e32 v7, 4, v62
	v_lshlrev_b32_e32 v174, 5, v0
	s_add_u32 s39, s73, s0
	v_bfe_u32 v201, v6, 5, 1
	v_add_u32_e32 v204, v1, v7
	v_or_b32_e32 v2, v174, v200
	v_mov_b64_e32 v[0:1], s[30:31]
	s_movk_i32 s0, 0x1800
	v_mad_i64_i32 v[0:1], s[0:1], v2, s0, v[0:1]
	v_lshlrev_b32_e32 v176, 4, v201
	v_mov_b32_e32 v177, v171
	v_lshl_add_u64 v[4:5], v[0:1], 0, v[176:177]
	global_load_dwordx4 v[0:3], v[4:5], off
	v_lshlrev_b32_e32 v12, 3, v6
	s_movk_i32 s1, 0xe0
	s_mov_b32 s0, 0x7ffffc
	s_addc_u32 s42, s63, 0
	s_cmp_lg_u32 0x100, -1
	s_mul_i32 s44, s38, 0x1800
	s_mul_hi_i32 s43, s38, 0x1800
	v_and_b32_e32 v8, 0x70, v6
	v_lshlrev_b32_e32 v72, 7, v200
	v_and_b32_e32 v73, 0x70, v12
	v_or_b32_e32 v64, 32, v176
	v_bitop3_b32 v64, v64, v72, v73 bitop3:0xde
	v_add_u32_e32 v209, 0x100, v64
	s_mov_b32 s5, s4
	s_mov_b32 s10, s4
	s_mov_b32 s11, s4
	s_mov_b32 s12, s4
	s_mov_b32 s13, s4
	s_mov_b32 s14, s4
	s_mov_b32 s15, s4
	s_mov_b32 s16, s4
	s_mov_b32 s17, s4
	s_mov_b32 s18, s4
	s_mov_b32 s19, s4
	v_mov_b32_e32 v61, v171
	v_cmp_gt_u32_e64 s[40:41], 32, v62
	s_mov_b32 s50, 4
	s_movk_i32 s51, 0xc0
	v_lshl_add_u32 v177, v200, 2, v175
	v_mov_b32_e32 v178, 0
	s_waitcnt vmcnt(0)
	ds_write_b128 v204, v[0:3] offset:51200
	global_load_dwordx4 v[0:3], v[4:5], off offset:32
	s_waitcnt vmcnt(0)
	ds_write_b128 v204, v[0:3] offset:52224
	global_load_dwordx4 v[0:3], v[4:5], off offset:64
	s_waitcnt vmcnt(0)
	ds_write_b128 v204, v[0:3] offset:53248
	global_load_dwordx4 v[0:3], v[4:5], off offset:96
	v_and_b32_e32 v5, 24, v12
	s_waitcnt vmcnt(0)
	ds_write_b128 v204, v[0:3] offset:54272
	v_ashrrev_i32_e32 v0, 4, v6
	v_lshlrev_b32_e32 v4, 5, v0
	v_lshrrev_b32_e32 v2, 5, v6
	v_bfe_u32 v3, v12, 5, 2
	v_and_or_b32 v4, v4, s1, v5
	v_and_or_b32 v2, v2, s0, v3
	v_lshlrev_b32_e32 v4, 1, v4
	v_lshl_or_b32 v13, v2, 9, v4
	v_add_u32_e32 v2, 32, v0
	v_lshrrev_b32_e32 v2, 1, v2
	v_and_or_b32 v2, v2, s0, v3
	s_movk_i32 s0, 0xc00
	v_and_b32_e32 v1, 0x78, v12
	v_mul_lo_u32 v0, v0, s0
	v_lshl_or_b32 v14, v2, 9, v4
	v_ashrrev_i32_e32 v2, 3, v6
	v_or_b32_e32 v0, v0, v1
	v_and_b32_e32 v3, 56, v12
	v_lshlrev_b32_e32 v170, 1, v0
	v_mul_lo_u32 v0, v2, s0
	v_or_b32_e32 v0, v0, v3
	s_cselect_b32 s0, 0x100, 0
	s_add_u32 s6, s39, s44
	v_lshlrev_b32_e32 v4, 7, v2
	v_lshlrev_b32_e32 v5, 1, v3
	v_lshlrev_b32_e32 v60, 1, v0
	v_lshlrev_b32_e32 v0, 3, v62
	v_and_b32_e32 v1, 0xc0, v7
	v_lshlrev_b32_e32 v2, 1, v6
	s_addc_u32 s7, s42, s43
	v_bitop3_b32 v15, v5, v4, v8 bitop3:0xde
	v_and_or_b32 v1, v0, 24, v1
	v_and_b32_e32 v2, 32, v2
	v_and_b32_e32 v0, 0x100, v0
	v_lshl_add_u64 v[4:5], s[6:7], 0, v[170:171]
	v_or3_b32 v63, v1, v2, v0
	s_add_u32 s8, s28, s44
	global_load_dwordx4 v[0:3], v170, s[6:7]
	v_add_co_u32_e32 v4, vcc, s33, v4
	s_addc_u32 s9, s29, s43
	s_nop 0
	v_addc_co_u32_e32 v5, vcc, 0, v5, vcc
	global_load_dwordx4 v[4:7], v[4:5], off
	v_add_u32_e32 v205, 0x100, v13
	global_load_dwordx4 v[8:11], v60, s[8:9]
	s_waitcnt vmcnt(0)
	v_add_u32_e32 v206, 0x100, v14
	v_add_u32_e32 v207, 0x100, v15
	s_mov_b32 s6, s4
	s_mov_b32 s7, s4
	s_mov_b32 s8, s4
	s_mov_b32 s9, s4
	s_add_i32 s1, s38, 64
	v_add_u32_e32 v203, s0, v63
	v_lshl_add_u64 v[180:181], s[28:29], 0, v[60:61]
	s_waitcnt vmcnt(2)
	ds_write_b128 v205, v[0:3]
	v_bitop3_b32 v0, v176, v72, v73 bitop3:0xde
	v_add_u32_e32 v208, 0x100, v0
	s_waitcnt vmcnt(1)
	ds_write_b128 v206, v[4:7]
	s_waitcnt vmcnt(0)
	ds_write_b128 v207, v[8:11] offset:32768
	s_waitcnt lgkmcnt(0)
	s_barrier
	ds_read_b128 v[56:59], v204 offset:52224
	ds_read_b128 v[52:55], v204 offset:53248
	ds_read_b128 v[48:51], v204 offset:54272
	ds_read_b128 v[16:19], v208 offset:36864
	ds_read_b128 v[20:23], v208 offset:32768
	ds_read_b128 v[24:27], v204 offset:51200
	s_waitcnt lgkmcnt(0)
	v_mfma_f32_32x32x16_bf16 v[32:47], v[20:23], v[24:27], 0
	ds_read_b128 v[64:67], v209 offset:36864
	ds_read_b128 v[68:71], v209 offset:32768
	v_mov_b64_e32 v[0:1], s[4:5]
	v_mov_b64_e32 v[2:3], s[6:7]
	v_mov_b64_e32 v[4:5], s[8:9]
	v_mov_b64_e32 v[6:7], s[10:11]
	v_mov_b64_e32 v[8:9], s[12:13]
	v_mov_b64_e32 v[10:11], s[14:15]
	v_mfma_f32_32x32x16_bf16 v[16:31], v[16:19], v[24:27], 0
	v_mov_b64_e32 v[12:13], s[16:17]
	v_mov_b64_e32 v[14:15], s[18:19]
	s_add_i32 s12, s44, 0x60000
	s_mul_hi_i32 s5, s1, 0x1800
	s_add_u32 s6, s39, s12
	s_addc_u32 s7, s42, s5
	s_add_u32 s8, s28, s12
	s_waitcnt lgkmcnt(0)
	v_mfma_f32_32x32x16_bf16 v[32:47], v[68:71], v[56:59], v[32:47]
	s_addc_u32 s9, s29, s5
	s_add_i32 s1, s38, 0x80
	s_add_i32 s47, s44, 0xc0000
	s_mul_hi_i32 s46, s1, 0x1800
	v_mfma_f32_32x32x16_bf16 v[16:31], v[64:67], v[56:59], v[16:31]
	v_or_b32_e32 v56, 64, v176
	v_bitop3_b32 v56, v56, v72, v73 bitop3:0xde
	v_add_u32_e32 v210, 0x100, v56
	ds_read_b128 v[56:59], v210 offset:36864
	ds_read_b128 v[64:67], v210 offset:32768
	s_waitcnt lgkmcnt(0)
	v_mfma_f32_32x32x16_bf16 v[32:47], v[64:67], v[52:55], v[32:47]
	v_mfma_f32_32x32x16_bf16 v[16:31], v[56:59], v[52:55], v[16:31]
	v_or_b32_e32 v52, 0x60, v176
	v_bitop3_b32 v52, v52, v72, v73 bitop3:0xde
	v_add_u32_e32 v211, 0x100, v52
	ds_read_b128 v[52:55], v211 offset:36864
	ds_read_b128 v[56:59], v211 offset:32768
	s_waitcnt lgkmcnt(0)
	v_mfma_f32_32x32x16_bf16 v[32:47], v[56:59], v[48:51], v[32:47]
	v_mfma_f32_32x32x16_bf16 v[16:31], v[52:55], v[48:51], v[16:31]
	s_nop 10
	v_max_f32_e32 v48, v33, v33
	v_max_f32_e32 v49, v32, v32
	v_max_f32_e32 v48, v49, v48
	v_max3_f32 v48, v48, v34, v35
	v_max3_f32 v48, v48, v36, v37
	v_max3_f32 v48, v48, v38, v39
	v_max3_f32 v48, v48, v40, v41
	v_max3_f32 v48, v48, v42, v43
	v_max3_f32 v48, v48, v44, v45
	v_max3_f32 v48, v48, v46, v47
	v_max3_f32 v48, v48, v16, v17
	v_max3_f32 v48, v48, v18, v19
	v_max3_f32 v48, v48, v20, v21
	v_max3_f32 v48, v48, v22, v23
	v_max3_f32 v48, v48, v24, v25
	v_max3_f32 v48, v48, v26, v27
	v_max3_f32 v48, v48, v28, v29
	v_max3_f32 v48, v48, v30, v31
	v_mov_b32_e32 v49, v48
	s_nop 1
	v_permlane32_swap_b32_e32 v48, v49
	v_max_f32_e32 v49, v49, v49
	v_max_f32_e32 v48, v48, v48
	v_max_f32_e32 v48, v48, v49
	v_sub_f32_e32 v36, v36, v48
	v_sub_f32_e32 v37, v37, v48
	v_exp_f32_e32 v53, v36
	v_exp_f32_e32 v54, v37
	v_lshl_add_u64 v[36:37], s[6:7], 0, v[170:171]
	v_add_co_u32_e32 v36, vcc, s33, v36
	v_sub_f32_e32 v32, v32, v48
	v_sub_f32_e32 v33, v33, v48
	v_sub_f32_e32 v34, v34, v48
	v_sub_f32_e32 v35, v35, v48
	v_sub_f32_e32 v38, v38, v48
	v_sub_f32_e32 v39, v39, v48
	v_sub_f32_e32 v40, v40, v48
	v_sub_f32_e32 v41, v41, v48
	v_sub_f32_e32 v42, v42, v48
	v_sub_f32_e32 v43, v43, v48
	v_sub_f32_e32 v44, v44, v48
	v_sub_f32_e32 v45, v45, v48
	v_sub_f32_e32 v46, v46, v48
	v_sub_f32_e32 v47, v47, v48
	v_addc_co_u32_e32 v37, vcc, 0, v37, vcc
	v_exp_f32_e32 v49, v32
	v_exp_f32_e32 v50, v33
	v_exp_f32_e32 v51, v34
	v_exp_f32_e32 v52, v35
	v_exp_f32_e32 v55, v38
	v_exp_f32_e32 v56, v39
	v_exp_f32_e32 v57, v40
	v_exp_f32_e32 v58, v41
	v_exp_f32_e32 v59, v42
	v_exp_f32_e32 v64, v43
	v_exp_f32_e32 v65, v44
	v_exp_f32_e32 v66, v45
	v_exp_f32_e32 v46, v46
	v_exp_f32_e32 v47, v47
	v_cvt_pk_bf16_f32 v144, v49, v50
	v_cvt_pk_bf16_f32 v145, v51, v52
	v_cvt_pk_bf16_f32 v146, v53, v54
	v_cvt_pk_bf16_f32 v147, v55, v56
	v_cvt_pk_bf16_f32 v140, v57, v58
	v_cvt_pk_bf16_f32 v141, v59, v64
	v_cvt_pk_bf16_f32 v142, v65, v66
	v_cvt_pk_bf16_f32 v143, v46, v47
	global_load_dwordx4 v[32:35], v170, s[6:7]
	s_nop 0
	global_load_dwordx4 v[36:39], v[36:37], off
	s_nop 0
	global_load_dwordx4 v[40:43], v60, s[8:9]
	v_writelane_b32 v253, s96, 0
	v_writelane_b32 v253, s97, 1
	v_mbcnt_lo_u32_b32 v131, -1, 0
	v_mbcnt_hi_u32_b32 v131, -1, v131
	v_readfirstlane_b32 s96, v168
	s_nop 3
	s_lshr_b32 s96, s96, 6
	s_movk_i32 s97, 0x1800
	v_lshrrev_b32_e32 v132, 3, v131
	v_lshl_add_u32 v132, s96, 3, v132
	v_bfe_u32 v133, v132, 1, 3
	v_and_b32_e32 v134, 7, v131
	v_xor_b32_e32 v133, v134, v133
	v_lshlrev_b32_e32 v133, 4, v133
	v_mad_u32_u24 v128, v132, s97, v133
	v_bfe_u32 v132, v131, 2, 3
	v_lshl_add_u32 v132, s96, 3, v132
	v_lshrrev_b32_e32 v133, 5, v131
	v_lshlrev_b32_e32 v133, 2, v133
	v_and_b32_e32 v134, 3, v131
	v_add_u32_e32 v133, v133, v134
	v_lshlrev_b32_e32 v133, 4, v133
	v_mad_u32_u24 v129, v132, s97, v133
	v_add_u32_e32 v130, 0x80, v129
	s_lshl_b32 s97, s96, 10
	s_lshl_b32 s96, s96, 11
	s_add_u32 s6, s28, s47
	s_addc_u32 s7, s29, s46
	s_add_i32 m0, s97, 0x20110
	s_nop 0
	global_load_lds_dwordx4 v128, s[6:7]
	s_add_u32 s6, s39, s47
	s_addc_u32 s7, s42, s46
	s_add_i32 m0, s96, 0x14900
	s_nop 0
	global_load_lds_dwordx4 v129, s[6:7]
	s_add_i32 m0, s96, 0x14d00
	s_nop 0
	global_load_lds_dwordx4 v130, s[6:7]
	v_add_f32_e32 v212, 0, v48
	s_nop 0
	s_waitcnt vmcnt(3)
	s_waitcnt vmcnt(5)
	ds_write_b128 v205, v[32:35] offset:16384
	s_waitcnt vmcnt(4)
	ds_write_b128 v206, v[36:39] offset:16384
	s_waitcnt vmcnt(3)
	ds_write_b128 v207, v[40:43] offset:40960
	v_add_f32_e32 v32, 0, v49
	v_add_f32_e32 v32, v50, v32
	v_add_f32_e32 v32, v51, v32
	v_add_f32_e32 v32, v52, v32
	v_add_f32_e32 v32, v53, v32
	v_add_f32_e32 v32, v54, v32
	v_add_f32_e32 v32, v55, v32
	v_add_f32_e32 v32, v56, v32
	v_add_f32_e32 v32, v57, v32
	v_add_f32_e32 v32, v58, v32
	v_add_f32_e32 v32, v59, v32
	v_add_f32_e32 v32, v64, v32
	v_add_f32_e32 v32, v65, v32
	v_add_f32_e32 v32, v66, v32
	v_add_f32_e32 v32, v46, v32
	s_addk_i32 s0, 0x4000
	v_xor_b32_e32 v96, 0x80000000, v212
	v_add_f32_e32 v164, v47, v32
	v_sub_f32_e32 v95, v31, v48
	v_sub_f32_e32 v94, v30, v48
	v_sub_f32_e32 v93, v29, v48
	v_sub_f32_e32 v92, v28, v48
	v_sub_f32_e32 v91, v27, v48
	v_sub_f32_e32 v90, v26, v48
	v_sub_f32_e32 v89, v25, v48
	v_sub_f32_e32 v88, v24, v48
	v_sub_f32_e32 v87, v23, v48
	v_sub_f32_e32 v86, v22, v48
	v_sub_f32_e32 v85, v21, v48
	v_sub_f32_e32 v84, v20, v48
	v_sub_f32_e32 v83, v19, v48
	v_sub_f32_e32 v82, v18, v48
	v_sub_f32_e32 v81, v17, v48
	v_sub_f32_e32 v80, v16, v48
	v_add_u32_e32 v202, s0, v63
	v_mov_b64_e32 v[62:63], v[14:15]
	v_mov_b64_e32 v[46:47], v[14:15]
	v_mov_b64_e32 v[30:31], v[14:15]
	s_mov_b64 s[8:9], 0
	v_mov_b64_e32 v[60:61], v[12:13]
	v_mov_b64_e32 v[58:59], v[10:11]
	v_mov_b64_e32 v[56:57], v[8:9]
	v_mov_b64_e32 v[54:55], v[6:7]
	v_mov_b64_e32 v[52:53], v[4:5]
	v_mov_b64_e32 v[50:51], v[2:3]
	v_mov_b64_e32 v[48:49], v[0:1]
	v_mov_b64_e32 v[44:45], v[12:13]
	v_mov_b64_e32 v[42:43], v[10:11]
	v_mov_b64_e32 v[40:41], v[8:9]
	v_mov_b64_e32 v[38:39], v[6:7]
	v_mov_b64_e32 v[36:37], v[4:5]
	v_mov_b64_e32 v[34:35], v[2:3]
	v_mov_b64_e32 v[32:33], v[0:1]
	v_mov_b64_e32 v[28:29], v[12:13]
	v_mov_b64_e32 v[26:27], v[10:11]
	v_mov_b64_e32 v[24:25], v[8:9]
	v_mov_b64_e32 v[22:23], v[6:7]
	v_mov_b64_e32 v[20:21], v[4:5]
	v_mov_b64_e32 v[18:19], v[2:3]
	v_mov_b64_e32 v[16:17], v[0:1]
	v_mov_b32_e32 v97, v96
	v_mov_b32_e32 v98, v96
	v_mov_b32_e32 v99, v96
	v_mov_b32_e32 v100, v96
	v_mov_b32_e32 v101, v96
	v_mov_b32_e32 v102, v96
	v_mov_b32_e32 v103, v96
	v_mov_b32_e32 v104, v96
	v_mov_b32_e32 v105, v96
	v_mov_b32_e32 v106, v96
	v_mov_b32_e32 v107, v96
	v_mov_b32_e32 v108, v96
	v_mov_b32_e32 v109, v96
	v_mov_b32_e32 v110, v96
	v_mov_b32_e32 v111, v96
	s_waitcnt lgkmcnt(0)
	s_barrier
	s_mov_b32 s100, 0x14800
	s_mov_b32 s101, 0x18010
	v_add_u32_e32 v205, s100, v205
	v_add_u32_e32 v206, s100, v206
	v_add_u32_e32 v207, s101, v207
	ds_read_b128 v[64:67], v204 offset:51200
	ds_read_b128 v[68:71], v204 offset:52224
	ds_read_b128 v[72:75], v204 offset:53248
	ds_read_b128 v[76:79], v204 offset:54272
	s_waitcnt lgkmcnt(0)

.LBB0_400:
	v_cvt_pk_bf16_f32 v182, v148, v149
	v_cvt_pk_bf16_f32 v183, v152, v153
	v_cvt_pk_bf16_f32 v184, v154, v155
	v_cvt_pk_bf16_f32 v185, v158, v159
	v_cvt_pk_bf16_f32 v160, v150, v151
	v_cvt_pk_bf16_f32 v161, v156, v157
	v_cvt_pk_bf16_f32 v162, v162, v163
	v_cvt_pk_bf16_f32 v163, v166, v167
	s_cmpk_lt_u32 s51, 0x100
	s_cselect_b32 s0, s38, s34
	s_add_i32 s3, s0, s51
	s_mul_i32 s0, s3, 0x1800
	s_mul_hi_i32 s1, s3, 0x1800
	s_add_u32 s0, s39, s0
	s_addc_u32 s1, s42, s1
	s_max_i32 vcc_lo, s100, 0
	s_add_i32 vcc_lo, vcc_lo, s96
	s_add_i32 m0, vcc_lo, 0x4100
	s_nop 0
	global_load_lds_dwordx4 v129, s[0:1]
	s_add_i32 m0, vcc_lo, 0x4500
	s_nop 0
	global_load_lds_dwordx4 v130, s[0:1]
	s_mul_i32 s0, s3, 0x1800
	s_mul_hi_i32 s1, s3, 0x1800
	s_add_u32 s0, s28, s0
	s_addc_u32 s1, s29, s1
	s_max_i32 vcc_lo, s101, 0
	s_add_i32 vcc_lo, vcc_lo, s97
	s_add_i32 m0, vcc_lo, 0xa100
	s_nop 0
	global_load_lds_dwordx4 v128, s[0:1]
	ds_read_b64_tr_b16 v[186:187], v203 offset:0
	ds_read_b64_tr_b16 v[188:189], v203 offset:0x800
	ds_read_b64_tr_b16 v[214:215], v203 offset:0x200
	ds_read_b64_tr_b16 v[216:217], v203 offset:0xa00
	ds_read_b64_tr_b16 v[218:219], v203 offset:0x400
	ds_read_b64_tr_b16 v[220:221], v203 offset:0xc00
	ds_read_b64_tr_b16 v[222:223], v203 offset:0x600
	ds_read_b64_tr_b16 v[224:225], v203 offset:0xe00
	ds_read_b64_tr_b16 v[226:227], v203 offset:0x1000
	ds_read_b64_tr_b16 v[228:229], v203 offset:0x1800
	ds_read_b64_tr_b16 v[230:231], v203 offset:0x1200
	ds_read_b64_tr_b16 v[232:233], v203 offset:0x1a00
	ds_read_b64_tr_b16 v[234:235], v203 offset:0x1400
	ds_read_b64_tr_b16 v[236:237], v203 offset:0x1c00
	ds_read_b64_tr_b16 v[238:239], v203 offset:0x1600
	ds_read_b64_tr_b16 v[240:241], v203 offset:0x1e00
	s_nop 0
	s_waitcnt lgkmcnt(8)
	v_exp_f32_e32 v112, v112
	v_mfma_f32_32x32x16_bf16 v[0:15], v[144:147], v[186:189], v[0:15]
	v_exp_f32_e32 v113, v113
	v_exp_f32_e32 v114, v114
	v_exp_f32_e32 v115, v115
	v_exp_f32_e32 v116, v116
	v_exp_f32_e32 v117, v117
	v_exp_f32_e32 v118, v118
	v_exp_f32_e32 v119, v119
	v_mfma_f32_32x32x16_bf16 v[48:63], v[144:147], v[214:217], v[48:63]
	v_exp_f32_e32 v120, v120
	v_exp_f32_e32 v121, v121
	v_exp_f32_e32 v122, v122
	v_exp_f32_e32 v123, v123
	v_exp_f32_e32 v124, v124
	v_exp_f32_e32 v125, v125
	v_exp_f32_e32 v126, v126
	v_mfma_f32_32x32x16_bf16 v[32:47], v[144:147], v[218:221], v[32:47]
	v_exp_f32_e32 v127, v127
	v_mfma_f32_32x32x16_bf16 v[16:31], v[144:147], v[222:225], v[16:31]
	ds_read_b64_tr_b16 v[144:145], v203 offset:0x2000
	ds_read_b64_tr_b16 v[146:147], v203 offset:0x2800
	ds_read_b64_tr_b16 v[186:187], v203 offset:0x2200
	ds_read_b64_tr_b16 v[188:189], v203 offset:0x2a00
	ds_read_b64_tr_b16 v[214:215], v203 offset:0x2400
	ds_read_b64_tr_b16 v[216:217], v203 offset:0x2c00
	ds_read_b64_tr_b16 v[218:219], v203 offset:0x2600
	ds_read_b64_tr_b16 v[220:221], v203 offset:0x2e00
	s_waitcnt lgkmcnt(8)
	ds_read_b64_tr_b16 v[222:223], v203 offset:0x3000
	ds_read_b64_tr_b16 v[224:225], v203 offset:0x3800
	s_nop 0
	v_mfma_f32_32x32x16_bf16 v[0:15], v[140:143], v[226:229], v[0:15]
	ds_read_b64_tr_b16 v[226:227], v203 offset:0x3200
	ds_read_b64_tr_b16 v[228:229], v203 offset:0x3a00
	v_mfma_f32_32x32x16_bf16 v[48:63], v[140:143], v[230:233], v[48:63]
	ds_read_b64_tr_b16 v[230:231], v203 offset:0x3400
	ds_read_b64_tr_b16 v[232:233], v203 offset:0x3c00
	v_mfma_f32_32x32x16_bf16 v[32:47], v[140:143], v[234:237], v[32:47]
	ds_read_b64_tr_b16 v[234:235], v203 offset:0x3600
	ds_read_b64_tr_b16 v[236:237], v203 offset:0x3e00
	s_waitcnt lgkmcnt(8)
	s_nop 0
	s_waitcnt lgkmcnt(0)
	v_mfma_f32_32x32x16_bf16 v[16:31], v[140:143], v[238:241], v[16:31]
	v_add_f32_e32 v140, 0, v112
	v_add_f32_e32 v140, v113, v140
	v_add_f32_e32 v140, v114, v140
	v_add_f32_e32 v140, v115, v140
	v_add_f32_e32 v140, v116, v140
	v_add_f32_e32 v140, v117, v140
	v_add_f32_e32 v140, v118, v140
	v_mfma_f32_32x32x16_bf16 v[0:15], v[182:185], v[144:147], v[0:15]
	v_add_f32_e32 v140, v119, v140
	v_add_f32_e32 v140, v120, v140
	v_add_f32_e32 v140, v121, v140
	v_add_f32_e32 v140, v122, v140
	v_add_f32_e32 v140, v123, v140
	v_add_f32_e32 v140, v124, v140
	v_add_f32_e32 v140, v125, v140
	v_mfma_f32_32x32x16_bf16 v[48:63], v[182:185], v[186:189], v[48:63]
	v_add_f32_e32 v140, v126, v140
	v_add_f32_e32 v165, v127, v140
	v_cvt_pk_bf16_f32 v144, v112, v113
	v_cvt_pk_bf16_f32 v145, v114, v115
	v_cvt_pk_bf16_f32 v146, v116, v117
	v_cvt_pk_bf16_f32 v147, v118, v119
	v_cvt_pk_bf16_f32 v140, v120, v121
	v_mfma_f32_32x32x16_bf16 v[32:47], v[182:185], v[214:217], v[32:47]
	v_cvt_pk_bf16_f32 v141, v122, v123
	v_cvt_pk_bf16_f32 v142, v124, v125
	v_cvt_pk_bf16_f32 v143, v126, v127
	v_mfma_f32_32x32x16_bf16 v[16:31], v[182:185], v[218:221], v[16:31]
	s_waitcnt vmcnt(3)
	s_waitcnt lgkmcnt(0)
	s_barrier
	v_mfma_f32_32x32x16_bf16 v[0:15], v[160:163], v[222:225], v[0:15]
	v_mfma_f32_32x32x16_bf16 v[48:63], v[160:163], v[226:229], v[48:63]
	v_mfma_f32_32x32x16_bf16 v[32:47], v[160:163], v[230:233], v[32:47]
	v_mfma_f32_32x32x16_bf16 v[16:31], v[160:163], v[234:237], v[16:31]
	v_add_u32_e32 v208, s101, v208
	v_add_u32_e32 v209, s101, v209
	v_add_u32_e32 v210, s101, v210
	v_add_u32_e32 v211, s101, v211
	ds_read_b128 v[160:163], v208 offset:32768
	ds_read_b128 v[222:225], v208 offset:36864
	v_exp_f32_e32 v166, v84
	v_exp_f32_e32 v167, v85
	s_waitcnt lgkmcnt(1)
	v_mfma_f32_32x32x16_bf16 v[112:127], v[160:163], v[64:67], v[96:111]
	ds_read_b128 v[160:163], v209 offset:32768
	ds_read_b128 v[226:229], v209 offset:36864
	ds_read_b128 v[238:241], v210 offset:36864
	ds_read_b128 v[182:185], v210 offset:32768
	ds_read_b128 v[242:245], v211 offset:36864
	ds_read_b128 v[188:191], v211 offset:32768
	v_exp_f32_e32 v186, v90
	v_exp_f32_e32 v187, v91
	s_andn2_b64 s[0:1], s[6:7], exec
	s_and_b64 s[6:7], s[8:9], exec
	s_or_b64 s[6:7], s[0:1], s[6:7]
	s_waitcnt lgkmcnt(5)
	v_mfma_f32_32x32x16_bf16 v[112:127], v[160:163], v[68:71], v[112:127]
	v_exp_f32_e32 v160, v80
	v_exp_f32_e32 v161, v81
	v_exp_f32_e32 v162, v82
	v_exp_f32_e32 v163, v83
	v_add_f32_e32 v80, v160, v165
	v_add_f32_e32 v80, v161, v80
	v_add_f32_e32 v165, v162, v80
	s_waitcnt lgkmcnt(2)
	v_mfma_f32_32x32x16_bf16 v[112:127], v[182:185], v[72:75], v[112:127]
	v_exp_f32_e32 v182, v86
	v_exp_f32_e32 v183, v87
	v_exp_f32_e32 v184, v88
	v_exp_f32_e32 v185, v89
	v_add_f32_e32 v165, v163, v165
	v_add_f32_e32 v165, v166, v165
	v_add_f32_e32 v165, v167, v165
	s_waitcnt lgkmcnt(0)
	v_mfma_f32_32x32x16_bf16 v[112:127], v[188:191], v[76:79], v[112:127]
	v_exp_f32_e32 v188, v92
	v_exp_f32_e32 v189, v93
	v_exp_f32_e32 v190, v94
	v_exp_f32_e32 v191, v95
	v_add_f32_e32 v165, v182, v165
	v_add_f32_e32 v165, v183, v165
	v_add_f32_e32 v165, v184, v165
	v_mfma_f32_32x32x16_bf16 v[80:95], v[222:225], v[64:67], v[96:111]
	v_add_f32_e32 v165, v185, v165
	v_add_f32_e32 v165, v186, v165
	v_add_f32_e32 v165, v187, v165
	v_add_f32_e32 v165, v188, v165
	v_add_f32_e32 v165, v189, v165
	v_add_f32_e32 v165, v190, v165
	v_add_f32_e32 v165, v191, v165
	v_mfma_f32_32x32x16_bf16 v[80:95], v[226:229], v[68:71], v[80:95]
	v_mov_b32_e32 v179, v165
	s_nop 1
	v_permlane32_swap_b32_e32 v165, v179
	v_add_f32_e64 v178, v164, v178
	v_add_f32_e64 v179, v165, v179
	v_cmp_ge_f32_e32 vcc, s99, v179
	s_cmp_eq_u64 vcc, exec
	v_mfma_f32_32x32x16_bf16 v[80:95], v[238:241], v[72:75], v[80:95]
	v_mfma_f32_32x32x16_bf16 v[80:95], v[242:245], v[76:79], v[80:95]
	s_cbranch_scc0 .LBB0_408
.LBB0_401:
	v_cvt_pk_bf16_f32 v164, v160, v161
	v_cvt_pk_bf16_f32 v165, v162, v163
	v_cvt_pk_bf16_f32 v166, v166, v167
	v_cvt_pk_bf16_f32 v167, v182, v183
	v_cvt_pk_bf16_f32 v160, v184, v185
	v_cvt_pk_bf16_f32 v161, v186, v187
	v_cvt_pk_bf16_f32 v162, v188, v189
	v_cvt_pk_bf16_f32 v163, v190, v191
	s_cmp_ge_u32 s50, s35
	s_cselect_b64 s[8:9], -1, 0
	s_and_b64 vcc, exec, s[8:9]
	s_cbranch_vccnz .LBB0_403
	s_add_i32 s0, s34, s51
	s_add_i32 s3, s0, 64
	s_mul_i32 s0, s3, 0x1800
	s_mul_hi_i32 s1, s3, 0x1800
	s_add_u32 s0, s39, s0
	s_addc_u32 s1, s42, s1
	s_sub_i32 vcc_lo, 0, s100
	s_max_i32 vcc_lo, vcc_lo, 0
	s_add_i32 vcc_lo, vcc_lo, s96
	s_add_i32 m0, vcc_lo, 0x100
	s_nop 0
	global_load_lds_dwordx4 v129, s[0:1]
	s_add_i32 m0, vcc_lo, 0x500
	s_nop 0
	global_load_lds_dwordx4 v130, s[0:1]
	s_mul_i32 s0, s3, 0x1800
	s_mul_hi_i32 s1, s3, 0x1800
	s_add_u32 s0, s28, s0
	s_addc_u32 s1, s29, s1
	s_sub_i32 vcc_lo, 0, s101
	s_max_i32 vcc_lo, vcc_lo, 0
	s_add_i32 vcc_lo, vcc_lo, s97
	s_add_i32 m0, vcc_lo, 0x8100
	s_nop 0
	global_load_lds_dwordx4 v128, s[0:1]
.LBB0_403:
	v_add_f32_e32 v178, v179, v178
	ds_read_b64_tr_b16 v[182:183], v202 offset:0
	ds_read_b64_tr_b16 v[184:185], v202 offset:0x800
	ds_read_b64_tr_b16 v[186:187], v202 offset:0x200
	ds_read_b64_tr_b16 v[188:189], v202 offset:0xa00
	ds_read_b64_tr_b16 v[214:215], v202 offset:0x400
	ds_read_b64_tr_b16 v[216:217], v202 offset:0xc00
	ds_read_b64_tr_b16 v[218:219], v202 offset:0x600
	ds_read_b64_tr_b16 v[220:221], v202 offset:0xe00
	ds_read_b64_tr_b16 v[222:223], v202 offset:0x1000
	ds_read_b64_tr_b16 v[224:225], v202 offset:0x1800
	ds_read_b64_tr_b16 v[226:227], v202 offset:0x1200
	ds_read_b64_tr_b16 v[228:229], v202 offset:0x1a00
	ds_read_b64_tr_b16 v[230:231], v202 offset:0x1400
	ds_read_b64_tr_b16 v[232:233], v202 offset:0x1c00
	ds_read_b64_tr_b16 v[234:235], v202 offset:0x1600
	ds_read_b64_tr_b16 v[236:237], v202 offset:0x1e00
	s_nop 0
	s_waitcnt lgkmcnt(8)
	v_exp_f32_e32 v112, v112
	v_mfma_f32_32x32x16_bf16 v[0:15], v[144:147], v[182:185], v[0:15]
	v_exp_f32_e32 v113, v113
	v_exp_f32_e32 v114, v114
	v_exp_f32_e32 v115, v115
	v_exp_f32_e32 v116, v116
	v_exp_f32_e32 v117, v117
	v_exp_f32_e32 v118, v118
	v_exp_f32_e32 v119, v119
	v_mfma_f32_32x32x16_bf16 v[48:63], v[144:147], v[186:189], v[48:63]
	v_exp_f32_e32 v120, v120
	v_exp_f32_e32 v121, v121
	v_exp_f32_e32 v122, v122
	v_exp_f32_e32 v123, v123
	v_exp_f32_e32 v124, v124
	v_exp_f32_e32 v125, v125
	v_exp_f32_e32 v126, v126
	v_mfma_f32_32x32x16_bf16 v[32:47], v[144:147], v[214:217], v[32:47]
	v_exp_f32_e32 v127, v127
	s_addk_i32 s51, 0x80
	s_add_i32 s50, s50, 2
	s_and_b64 vcc, exec, s[8:9]
	v_mfma_f32_32x32x16_bf16 v[16:31], v[144:147], v[218:221], v[16:31]
	ds_read_b64_tr_b16 v[144:145], v202 offset:0x2000
	ds_read_b64_tr_b16 v[146:147], v202 offset:0x2800
	ds_read_b64_tr_b16 v[182:183], v202 offset:0x2200
	ds_read_b64_tr_b16 v[184:185], v202 offset:0x2a00
	ds_read_b64_tr_b16 v[186:187], v202 offset:0x2400
	ds_read_b64_tr_b16 v[188:189], v202 offset:0x2c00
	ds_read_b64_tr_b16 v[214:215], v202 offset:0x2600
	ds_read_b64_tr_b16 v[216:217], v202 offset:0x2e00
	s_waitcnt lgkmcnt(8)
	ds_read_b64_tr_b16 v[218:219], v202 offset:0x3000
	ds_read_b64_tr_b16 v[220:221], v202 offset:0x3800
	s_nop 0
	v_mfma_f32_32x32x16_bf16 v[0:15], v[140:143], v[222:225], v[0:15]
	ds_read_b64_tr_b16 v[222:223], v202 offset:0x3200
	ds_read_b64_tr_b16 v[224:225], v202 offset:0x3a00
	v_mfma_f32_32x32x16_bf16 v[48:63], v[140:143], v[226:229], v[48:63]
	ds_read_b64_tr_b16 v[226:227], v202 offset:0x3400
	ds_read_b64_tr_b16 v[228:229], v202 offset:0x3c00
	v_mfma_f32_32x32x16_bf16 v[32:47], v[140:143], v[230:233], v[32:47]
	ds_read_b64_tr_b16 v[230:231], v202 offset:0x3600
	ds_read_b64_tr_b16 v[232:233], v202 offset:0x3e00
	s_waitcnt lgkmcnt(8)
	s_nop 0
	s_waitcnt lgkmcnt(0)
	v_mfma_f32_32x32x16_bf16 v[16:31], v[140:143], v[234:237], v[16:31]
	v_add_f32_e32 v140, 0, v112
	v_add_f32_e32 v140, v113, v140
	v_add_f32_e32 v140, v114, v140
	v_add_f32_e32 v140, v115, v140
	v_add_f32_e32 v140, v116, v140
	v_add_f32_e32 v140, v117, v140
	v_add_f32_e32 v140, v118, v140
	v_mfma_f32_32x32x16_bf16 v[0:15], v[164:167], v[144:147], v[0:15]
	v_add_f32_e32 v140, v119, v140
	v_add_f32_e32 v140, v120, v140
	v_add_f32_e32 v140, v121, v140
	v_add_f32_e32 v140, v122, v140
	v_add_f32_e32 v140, v123, v140
	v_add_f32_e32 v140, v124, v140
	v_add_f32_e32 v140, v125, v140
	v_mfma_f32_32x32x16_bf16 v[48:63], v[164:167], v[182:185], v[48:63]
	v_add_f32_e32 v140, v126, v140
	v_cvt_pk_bf16_f32 v144, v112, v113
	v_cvt_pk_bf16_f32 v145, v114, v115
	v_cvt_pk_bf16_f32 v146, v116, v117
	v_cvt_pk_bf16_f32 v147, v118, v119
	v_mfma_f32_32x32x16_bf16 v[32:47], v[164:167], v[186:189], v[32:47]
	v_mfma_f32_32x32x16_bf16 v[16:31], v[164:167], v[214:217], v[16:31]
	v_add_f32_e32 v164, v127, v140
	v_cvt_pk_bf16_f32 v140, v120, v121
	v_cvt_pk_bf16_f32 v141, v122, v123
	v_cvt_pk_bf16_f32 v142, v124, v125
	v_cvt_pk_bf16_f32 v143, v126, v127
	v_mfma_f32_32x32x16_bf16 v[0:15], v[160:163], v[218:221], v[0:15]
	s_waitcnt vmcnt(3)
	s_cbranch_vccz .Ldma_w3
	s_waitcnt vmcnt(0)
.Ldma_w3:
	s_waitcnt lgkmcnt(0)
	s_barrier
	v_mfma_f32_32x32x16_bf16 v[48:63], v[160:163], v[222:225], v[48:63]
	v_mfma_f32_32x32x16_bf16 v[32:47], v[160:163], v[226:229], v[32:47]
	v_mfma_f32_32x32x16_bf16 v[16:31], v[160:163], v[230:233], v[16:31]
	v_add_u32_e32 v202, s100, v202
	v_add_u32_e32 v203, s100, v203
	s_sub_i32 s100, 0, s100
	s_sub_i32 s101, 0, s101
	s_cbranch_vccnz .LBB0_411
	s_mov_b64 s[8:9], s[6:7]
	s_branch .LBB0_398

.LBB0_411:
	v_readlane_b32 s96, v253, 0
	v_readlane_b32 s97, v253, 1
	v_mov_b64_e32 v[64:65], v[96:97]
	v_mov_b64_e32 v[66:67], v[98:99]
	v_mov_b64_e32 v[68:69], v[100:101]
	v_mov_b64_e32 v[70:71], v[102:103]
	v_mov_b64_e32 v[72:73], v[104:105]
	v_mov_b64_e32 v[74:75], v[106:107]
	v_mov_b64_e32 v[76:77], v[108:109]
	v_mov_b64_e32 v[78:79], v[110:111]
	ds_read_b128 v[120:123], v204 offset:52224
	ds_read_b128 v[124:127], v204 offset:53248
	ds_read_b128 v[128:131], v204 offset:54272
	ds_read_b128 v[132:135], v208 offset:45056
	ds_read_b128 v[112:115], v208 offset:40960
	ds_read_b128 v[136:139], v204 offset:51200
	v_exp_f32_e32 v118, v82
	v_exp_f32_e32 v119, v83
	v_exp_f32_e32 v116, v84
	v_exp_f32_e32 v117, v85
	s_waitcnt lgkmcnt(0)
	v_mfma_f32_32x32x16_bf16 v[96:111], v[112:115], v[136:139], v[64:79]
	ds_read_b128 v[148:151], v209 offset:45056
	ds_read_b128 v[112:115], v209 offset:40960
	v_exp_f32_e32 v84, v92
	v_exp_f32_e32 v85, v93
	v_exp_f32_e32 v82, v94
	v_exp_f32_e32 v83, v95
	s_waitcnt lgkmcnt(0)
	v_mfma_f32_32x32x16_bf16 v[96:111], v[112:115], v[120:123], v[96:111]
	ds_read_b128 v[152:155], v210 offset:45056
	ds_read_b128 v[112:115], v210 offset:40960
	s_waitcnt lgkmcnt(0)
	v_mfma_f32_32x32x16_bf16 v[96:111], v[112:115], v[124:127], v[96:111]
	ds_read_b128 v[156:159], v211 offset:45056
	ds_read_b128 v[112:115], v211 offset:40960
	v_mfma_f32_32x32x16_bf16 v[64:79], v[132:135], v[136:139], v[64:79]
	s_waitcnt lgkmcnt(0)
	v_mfma_f32_32x32x16_bf16 v[96:111], v[112:115], v[128:131], v[96:111]
	v_exp_f32_e32 v112, v80
	v_exp_f32_e32 v113, v81
	v_exp_f32_e32 v80, v88
	v_exp_f32_e32 v114, v86
	v_add_f32_e32 v88, v112, v164
	v_add_f32_e32 v88, v113, v88
	v_add_f32_e32 v88, v118, v88
	v_mfma_f32_32x32x16_bf16 v[64:79], v[148:151], v[120:123], v[64:79]
	v_exp_f32_e32 v115, v87
	v_add_f32_e32 v88, v119, v88
	v_add_f32_e32 v88, v116, v88
	v_exp_f32_e32 v81, v89
	v_add_f32_e32 v88, v117, v88
	v_exp_f32_e32 v86, v90
	v_add_f32_e32 v88, v114, v88
	v_mfma_f32_32x32x16_bf16 v[64:79], v[152:155], v[124:127], v[64:79]
	v_exp_f32_e32 v87, v91
	v_add_f32_e32 v88, v115, v88
	v_add_f32_e32 v88, v80, v88
	v_add_f32_e32 v88, v81, v88
	v_add_f32_e32 v88, v86, v88
	v_add_f32_e32 v88, v87, v88
	v_add_f32_e32 v88, v84, v88
	v_add_f32_e32 v88, v85, v88
	v_mfma_f32_32x32x16_bf16 v[64:79], v[156:159], v[128:131], v[64:79]
	v_add_f32_e32 v88, v82, v88
	v_add_f32_e32 v88, v83, v88
	v_mov_b32_e32 v89, v88
	s_nop 1
	v_permlane32_swap_b32_e32 v88, v89
	v_add_f32_e32 v88, v88, v89
	v_cmp_ge_f32_e32 vcc, s99, v88
	s_cmp_lg_u64 vcc, exec
	s_cbranch_scc1 .LBB0_450

	.amdhsa_kernel _Z11mega_kernel6Paramsii
		.amdhsa_group_segment_fixed_size 16640
		.amdhsa_private_segment_fixed_size 0
		.amdhsa_kernarg_size 488
		.amdhsa_user_sgpr_count 2
		.amdhsa_user_sgpr_dispatch_ptr 0
		.amdhsa_user_sgpr_queue_ptr 0
		.amdhsa_user_sgpr_kernarg_segment_ptr 1
		.amdhsa_user_sgpr_dispatch_id 0
		.amdhsa_user_sgpr_kernarg_preload_length 0
		.amdhsa_user_sgpr_kernarg_preload_offset 0
		.amdhsa_user_sgpr_private_segment_size 0
		.amdhsa_uses_dynamic_stack 0
		.amdhsa_enable_private_segment 0
		.amdhsa_system_sgpr_workgroup_id_x 1
		.amdhsa_system_sgpr_workgroup_id_y 0
		.amdhsa_system_sgpr_workgroup_id_z 0
		.amdhsa_system_sgpr_workgroup_info 0
		.amdhsa_system_vgpr_workitem_id 2
		.amdhsa_next_free_vgpr 254
		.amdhsa_next_free_sgpr 102
		.amdhsa_accum_offset 256
		.amdhsa_reserve_vcc 1
		.amdhsa_float_round_mode_32 0
		.amdhsa_float_round_mode_16_64 0
		.amdhsa_float_denorm_mode_32 3
		.amdhsa_float_denorm_mode_16_64 3
		.amdhsa_dx10_clamp 1
		.amdhsa_ieee_mode 1
		.amdhsa_fp16_overflow 0
		.amdhsa_tg_split 0
		.amdhsa_exception_fp_ieee_invalid_op 0
		.amdhsa_exception_fp_denorm_src 0
		.amdhsa_exception_fp_ieee_div_zero 0
		.amdhsa_exception_fp_ieee_overflow 0
		.amdhsa_exception_fp_ieee_underflow 0
		.amdhsa_exception_fp_ieee_inexact 0
		.amdhsa_exception_int_div_zero 0
	.end_amdhsa_kernel

amdhsa.kernels:
  - .agpr_count:     0
    .args:
      - .offset:         0
        .size:           224
        .value_kind:     by_value
      - .offset:         224
        .size:           4
        .value_kind:     by_value
      - .offset:         228
        .size:           4
        .value_kind:     by_value
      - .offset:         232
        .size:           4
        .value_kind:     hidden_block_count_x
      - .offset:         236
        .size:           4
        .value_kind:     hidden_block_count_y
      - .offset:         240
        .size:           4
        .value_kind:     hidden_block_count_z
      - .offset:         244
        .size:           2
        .value_kind:     hidden_group_size_x
      - .offset:         246
        .size:           2
        .value_kind:     hidden_group_size_y
      - .offset:         248
        .size:           2
        .value_kind:     hidden_group_size_z
      - .offset:         250
        .size:           2
        .value_kind:     hidden_remainder_x
      - .offset:         252
        .size:           2
        .value_kind:     hidden_remainder_y
      - .offset:         254
        .size:           2
        .value_kind:     hidden_remainder_z
      - .offset:         272
        .size:           8
        .value_kind:     hidden_global_offset_x
      - .offset:         280
        .size:           8
        .value_kind:     hidden_global_offset_y
      - .offset:         288
        .size:           8
        .value_kind:     hidden_global_offset_z
      - .offset:         296
        .size:           2
        .value_kind:     hidden_grid_dims
      - .offset:         320
        .size:           8
        .value_kind:     hidden_multigrid_sync_arg
      - .offset:         352
        .size:           4
        .value_kind:     hidden_dynamic_lds_size
    .group_segment_fixed_size: 16640
    .kernarg_segment_align: 8
    .kernarg_segment_size: 488
    .language:       OpenCL C
    .language_version:
      - 2
      - 0
    .max_flat_workgroup_size: 512
    .name:           _Z11mega_kernel6Paramsii
    .private_segment_fixed_size: 0
    .sgpr_count:     108
    .sgpr_spill_count: 197
    .symbol:         _Z11mega_kernel6Paramsii.kd
    .uniform_work_group_size: 1
    .uses_dynamic_stack: false
    .vgpr_count:     254
    .vgpr_spill_count: 0
    .wavefront_size: 64
